# speedup vs baseline: 1.0147x; 1.0109x over previous
; DEV unsigned xb_ld(unsigned* p) { return __hip_atomic_load(p, __ATOMIC_RELAXED, __HIP_MEMORY_SCOPE_AGENT); }
; DEV unsigned xb_add(unsigned* p, unsigned v) { return __hip_atomic_fetch_add(p, v, __ATOMIC_RELAXED, __HIP_MEMORY_SCOPE_AGENT); }
; DEV unsigned xb_xcc_id() { return (unsigned)__builtin_amdgcn_s_getreg((3 << 11) | 20) & 0xFu; }
; #define XB_SPIN(cond, bar) do { unsigned _sp = 0; while (cond) { __builtin_amdgcn_s_sleep(1); \
;     if ((++_sp & 255u) == 0u) { if (xb_ld(&(bar)[XB_TMO])) break; if (_sp > XB_SPIN_CAP) { atomicAdd(&(bar)[XB_TMO], 1u); break; } } } } while (0)
;   uint4* sh = xb_state();
;   if (threadIdx.x == 0) {
;     const unsigned x = xb_xcc_id();
;     xb_add(&bar[XB_XCNT(x)], 1u);
;     __threadfence();
;     const unsigned G = gridDim.x * gridDim.y * gridDim.z;
;     const unsigned old = xb_add(&bar[XB_CNT], 1u), gen = old / G;
;     if (old + 1u == (gen + 1u) * G) xb_add(&bar[XB_GEN], 1u); else XB_SPIN(xb_ld(&bar[XB_GEN]) == gen, bar);
_Z6k_mega6Params:
	s_mov_b32 s100, 0
	s_load_dwordx2 s[28:29], s[0:1], 0x108
	s_load_dword s30, s[0:1], 0x110
	s_add_u32 s4, s0, 0x110
	v_writelane_b32 v254, s0, 0
	s_addc_u32 s5, s1, 0
	v_and_b32_e32 v197, 0x3ff, v0
	v_writelane_b32 v254, s1, 1
	v_writelane_b32 v254, s4, 2
	s_waitcnt lgkmcnt(0)
	s_add_u32 s0, s28, 0x1bd00000
	s_addc_u32 s1, s29, 0
	v_writelane_b32 v254, s5, 3
	v_writelane_b32 v254, s0, 4
	s_nop 1
	v_writelane_b32 v254, s1, 5
	v_cmp_eq_u32_e64 s[0:1], 0, v197
	s_nop 1
	v_writelane_b32 v254, s0, 6
	s_nop 1
	v_writelane_b32 v254, s1, 7
	s_and_saveexec_b64 s[26:27], s[0:1]
	s_cbranch_execz .LBB0_20
	v_readlane_b32 s0, v254, 2
	v_readlane_b32 s1, v254, 3
	s_load_dwordx2 s[6:7], s[0:1], 0x4
	s_getreg_b32 s4, hwreg(HW_REG_XCC_ID, 0, 4)
	s_mov_b64 s[8:9], exec
	s_and_b32 s24, s4, 15
	s_lshl_b32 s4, s24, 8
	v_readlane_b32 s0, v254, 4
	v_mbcnt_lo_u32_b32 v1, s8, 0
	v_readlane_b32 s1, v254, 5
	s_add_u32 s4, s0, s4
	v_mbcnt_hi_u32_b32 v1, s9, v1
	s_addc_u32 s5, s1, 0
	v_cmp_eq_u32_e32 vcc, 0, v1
	s_and_saveexec_b64 s[10:11], vcc
	s_cbranch_execz .LBB0_3
	s_bcnt1_i32_b64 s8, s[8:9]
	v_mov_b32_e32 v1, 0
	v_mov_b32_e32 v2, s8
	global_atomic_add v1, v2, s[4:5] offset:1024

; template <class Epi>
; DEV void gemm_phase(char* shm, const u16* __restrict__ A, const u16* __restrict__ Bt, int K, int nM, int nN, Epi epi) {
;     ...
;   for (int t = blockIdx.x; t < nfull + (ntail ? G : 0); t += G) {
;     const bool tail = t >= nfull;
;     int wgid = tail ? nfull + ((t - nfull) >> 1) : t;
;     { int q = nwg / NXCD, r = nwg % NXCD, xcd = wgid % NXCD, off = wgid / NXCD;
;       wgid = (xcd < r ? xcd * (q + 1) : r * (q + 1) + (xcd - r) * q) + off; }
;     int nig = WGM * nN, gid = wgid / nig, fm = gid * WGM, gsz = min(nM - fm, WGM);
;     int pm = fm + ((wgid % nig) % gsz), pn = (wgid % nig) / gsz;
;     int brow = pm * 256, bcol = pn * 256;
;     if (!tail) gemm_tile8(shm, A, Bt, K, brow, bcol, epi);
;     else {
;       brow += ((t - nfull) & 1) * 128;
;       gemm_tile<4>(shm, A + (long)brow * K, Bt + (long)bcol * K, K, brow, bcol, epi);
; DEV void run_phase(const Params& p_in, int ph, int layer, int half, char* smem) {
;     ...
;     case PH_UP: {
;       EpiUpN e; e.dst = (u16*)(ws + OFF_U); e.ss = (const float*)(ws + OFF_SSU);
;       gemm_phase(smem, (const u16*)(ws + OFF_XB), (const u16*)(ws + OFF_WUP), 1024, TH / 256, 22, e);
;     } break;
.LBB0_446:
	s_andn2_b64 vcc, exec, s[6:7]
	s_cbranch_vccnz .LBB0_571
	s_cmp_lt_i32 s80, 9
	s_mov_b64 s[6:7], -1
	s_cbranch_scc1 .LBB0_540
	s_cmp_gt_i32 s80, 10
	s_cbranch_scc0 .LBB0_477
	v_readlane_b32 s6, v254, 23
	v_readlane_b32 s7, v254, 24
	s_andn2_b64 vcc, exec, s[6:7]
	s_cbranch_vccnz .LBB0_476
	s_add_u32 s6, s38, 0x1dd4c000
	s_addc_u32 s7, s39, 0
	s_add_u32 s26, s38, 0x19c80000
	s_addc_u32 s27, s39, 0
	s_add_u32 s30, s38, 0xf00000
	s_addc_u32 s31, s39, 0
	s_add_u32 s18, s38, 0xf00080
	v_writelane_b32 v255, s6, 46
	s_addc_u32 s19, s39, 0
	s_add_u32 s20, s38, 0x19c80080
	v_writelane_b32 v255, s7, 47
	v_readlane_b32 s6, v254, 45
	s_addc_u32 s21, s39, 0
	v_readlane_b32 s40, v254, 28
	s_mov_b32 s41, s6
	s_mov_b32 s100, 0
	s_bitcmp1_b32 s41, 0
	s_cbranch_scc0 .Lstg_up_e
	v_readlane_b32 s101, v254, 21
	v_readlane_b32 s6, v254, 22
	s_cmp_eq_u32 s101, s6
	s_cbranch_scc1 .Lstg_up_e
	s_lshl_b32 s40, s41, 7
	s_add_i32 s41, s41, s101
	s_mov_b32 s100, 1
.Lstg_up_e:
	v_readlane_b32 s7, v254, 46
	s_branch .LBB0_452
.LBB0_451:
	s_cmp_eq_u32 s100, 1
	s_cbranch_scc0 .Lstg_up_l1
	s_mov_b32 s100, 2
	v_readlane_b32 s41, v254, 45
	v_readlane_b32 s40, v254, 28
	v_readlane_b32 s7, v254, 49
	s_branch .LBB0_452
.Lstg_up_l1:
	v_readlane_b32 s6, v254, 48
	s_add_i32 s41, s41, s6
	v_readlane_b32 s6, v254, 29
	s_add_i32 s40, s40, s6
	v_readlane_b32 s6, v254, 22
	s_cmp_eq_u32 s100, 2
	s_cbranch_scc0 .Lstg_up_l2
	v_readlane_b32 s6, v254, 21
.Lstg_up_l2:
	s_cmp_ge_i32 s41, s6
	v_readlane_b32 s7, v254, 49
	s_cbranch_scc1 .LBB0_476

; template <class Epi>
; DEV void gemm_phase(char* shm, const u16* __restrict__ A, const u16* __restrict__ Bt, int K, int nM, int nN, Epi epi) {
;     ...
;   for (int t = blockIdx.x; t < nfull + (ntail ? G : 0); t += G) {
;     const bool tail = t >= nfull;
;     int wgid = tail ? nfull + ((t - nfull) >> 1) : t;
; DEV void run_phase(const Params& p_in, int ph, int layer, int half, char* smem) {
;     ...
;     case PH_INPROJ: {
;       EpiInproj e;
;       e.q = (u16*)(ws + OFF_Q); e.k = (u16*)(ws + OFF_K); e.vt = (u16*)(ws + OFF_VT); e.zr = (u16*)(ws + OFF_ZR);
;       e.gates = (u16*)(ws + OFF_GATES); e.flog = (float*)(ws + OFF_FLOG); e.vd = (float*)(ws + OFF_VD);
;       e.gq = pp->in[I_GQ] + layer * 64; e.gk = pp->in[I_GK] + layer * 64; e.bf = pp->in[I_BF] + layer * 8;
;       gemm_phase(smem, HN, (const u16*)(ws + OFF_WIN), 1024, TH / 256, 22, e);
.LBB0_854:
	s_andn2_b64 vcc, exec, s[6:7]
	s_cbranch_vccnz .LBB0_1260
	s_cmp_lt_i32 s80, 1
	s_mov_b64 s[6:7], -1
	s_cbranch_scc1 .LBB0_989
	s_cmp_gt_i32 s80, 1
	s_cbranch_scc0 .LBB0_983
	v_readlane_b32 s6, v254, 23
	v_readlane_b32 s7, v254, 24
	s_andn2_b64 vcc, exec, s[6:7]
	s_cbranch_vccnz .LBB0_982
	v_readlane_b32 s6, v255, 30
	v_readlane_b32 s7, v255, 31
	s_and_b64 s[6:7], s[6:7], exec
	v_readlane_b32 s6, v255, 46
	v_readlane_b32 s7, v255, 47
	s_cselect_b32 s48, s95, s7
	s_cselect_b32 s81, s94, s6
	s_add_u32 s6, s38, 0x7200000
	v_writelane_b32 v255, s6, 46
	s_addc_u32 s6, s39, 0
	s_add_u32 s18, s38, 0x8200000
	s_addc_u32 s19, s39, 0
	v_writelane_b32 v255, s6, 44
	s_add_u32 s6, s38, 0x9280000
	s_addc_u32 s7, s39, 0
	v_writelane_b32 v255, s6, 48
	v_readlane_b32 s84, v254, 28
	s_nop 0
	v_writelane_b32 v255, s7, 49
	s_add_u32 s6, s38, 0xca80000
	s_addc_u32 s7, s39, 0
	v_writelane_b32 v255, s6, 50
	s_add_u32 s24, s38, 0x9200000
	s_addc_u32 s25, s39, 0
	v_writelane_b32 v255, s7, 51
	s_add_u32 s30, s38, 0x10a80000
	v_readlane_b32 s6, v255, 42
	v_readlane_b32 s7, v255, 43
	s_load_dwordx4 s[12:15], s[6:7], 0x20
	v_readlane_b32 s10, v255, 24
	s_load_dwordx2 s[6:7], s[6:7], 0x30
	v_readlane_b32 s11, v255, 25
	s_addc_u32 s31, s39, 0
	s_lshl_b64 s[10:11], s[10:11], 2
	s_waitcnt lgkmcnt(0)
	s_add_u32 s14, s14, s10
	v_writelane_b32 v255, s14, 52
	s_addc_u32 s14, s15, s11
	v_writelane_b32 v255, s14, 53
	s_add_u32 s6, s6, s10
	v_writelane_b32 v255, s6, 54
	s_addc_u32 s6, s7, s11
	v_writelane_b32 v255, s6, 55
	s_nop 0
	v_readlane_b32 s6, v255, 28
	v_readlane_b32 s7, v255, 29
	s_add_u32 s36, s12, s6
	s_addc_u32 s37, s13, s7
	s_add_u32 s40, s38, 0x80
	s_addc_u32 s41, s39, 0
	s_add_u32 s42, s81, 0x80
	v_readlane_b32 s6, v254, 45
	s_addc_u32 s43, s48, 0
	s_mov_b32 s85, s6
	s_mov_b32 s100, 0
	s_bitcmp1_b32 s85, 0
	s_cbranch_scc0 .Lstg_in_e
	v_readlane_b32 s101, v254, 21
	v_readlane_b32 s6, v254, 22
	s_cmp_eq_u32 s101, s6
	s_cbranch_scc1 .Lstg_in_e
	s_lshl_b32 s84, s85, 7
	s_add_i32 s85, s85, s101
	s_mov_b32 s100, 1

; template <class Epi>
; DEV void gemm_phase(char* shm, const u16* __restrict__ A, const u16* __restrict__ Bt, int K, int nM, int nN, Epi epi) {
;     ...
;   for (int t = blockIdx.x; t < nfull + (ntail ? G : 0); t += G) {
;     const bool tail = t >= nfull;
;     int wgid = tail ? nfull + ((t - nfull) >> 1) : t;
.LBB0_860:
	s_cmp_eq_u32 s100, 1
	s_cbranch_scc0 .Lstg_in_l1
	s_mov_b32 s100, 2
	v_readlane_b32 s85, v254, 45
	v_readlane_b32 s84, v254, 28
	v_readlane_b32 s7, v254, 49
	s_branch .LBB0_861
.Lstg_in_l1:
	v_readlane_b32 s6, v254, 48
	s_add_i32 s85, s85, s6
	v_readlane_b32 s6, v254, 29
	s_add_i32 s84, s84, s6
	v_readlane_b32 s6, v254, 22
	s_cmp_eq_u32 s100, 2
	s_cbranch_scc0 .Lstg_in_l2
	v_readlane_b32 s6, v254, 21
.Lstg_in_l2:
	s_cmp_ge_i32 s85, s6
	v_readlane_b32 s7, v254, 49
	s_cbranch_scc1 .LBB0_982

; __global__ void __launch_bounds__(NTHREADS) k_mega(Params p) {
;   __shared__ __attribute__((aligned(1024))) char smem[131072 + 1024];
	.amdhsa_kernel _Z6k_mega6Params
		.amdhsa_group_segment_fixed_size 132112
		.amdhsa_private_segment_fixed_size 0
		.amdhsa_kernarg_size 528
		.amdhsa_user_sgpr_count 2
		.amdhsa_user_sgpr_dispatch_ptr 0
		.amdhsa_user_sgpr_queue_ptr 0
		.amdhsa_user_sgpr_kernarg_segment_ptr 1
		.amdhsa_user_sgpr_dispatch_id 0
		.amdhsa_user_sgpr_kernarg_preload_length 0
		.amdhsa_user_sgpr_kernarg_preload_offset 0
		.amdhsa_user_sgpr_private_segment_size 0
		.amdhsa_uses_dynamic_stack 0
		.amdhsa_enable_private_segment 0
		.amdhsa_system_sgpr_workgroup_id_x 1
		.amdhsa_system_sgpr_workgroup_id_y 0
		.amdhsa_system_sgpr_workgroup_id_z 0
		.amdhsa_system_sgpr_workgroup_info 0
		.amdhsa_system_vgpr_workitem_id 2
		.amdhsa_next_free_vgpr 256
		.amdhsa_next_free_sgpr 102
		.amdhsa_accum_offset 256
		.amdhsa_reserve_vcc 1
		.amdhsa_float_round_mode_32 0
		.amdhsa_float_round_mode_16_64 0
		.amdhsa_float_denorm_mode_32 3
		.amdhsa_float_denorm_mode_16_64 3
		.amdhsa_dx10_clamp 1
		.amdhsa_ieee_mode 1
		.amdhsa_fp16_overflow 0
		.amdhsa_tg_split 0
		.amdhsa_exception_fp_ieee_invalid_op 0
		.amdhsa_exception_fp_denorm_src 0
		.amdhsa_exception_fp_ieee_div_zero 0
		.amdhsa_exception_fp_ieee_overflow 0
		.amdhsa_exception_fp_ieee_underflow 0
		.amdhsa_exception_fp_ieee_inexact 0
		.amdhsa_exception_int_div_zero 0
	.end_amdhsa_kernel

; __global__ void __launch_bounds__(NTHREADS) k_mega(Params p) {
;   __shared__ __attribute__((aligned(1024))) char smem[131072 + 1024];
amdhsa.kernels:
  - .agpr_count:     0
    .args:
      - .offset:         0
        .size:           272
        .value_kind:     by_value
      - .offset:         272
        .size:           4
        .value_kind:     hidden_block_count_x
      - .offset:         276
        .size:           4
        .value_kind:     hidden_block_count_y
      - .offset:         280
        .size:           4
        .value_kind:     hidden_block_count_z
      - .offset:         284
        .size:           2
        .value_kind:     hidden_group_size_x
      - .offset:         286
        .size:           2
        .value_kind:     hidden_group_size_y
      - .offset:         288
        .size:           2
        .value_kind:     hidden_group_size_z
      - .offset:         290
        .size:           2
        .value_kind:     hidden_remainder_x
      - .offset:         292
        .size:           2
        .value_kind:     hidden_remainder_y
      - .offset:         294
        .size:           2
        .value_kind:     hidden_remainder_z
      - .offset:         312
        .size:           8
        .value_kind:     hidden_global_offset_x
      - .offset:         320
        .size:           8
        .value_kind:     hidden_global_offset_y
      - .offset:         328
        .size:           8
        .value_kind:     hidden_global_offset_z
      - .offset:         336
        .size:           2
        .value_kind:     hidden_grid_dims
      - .offset:         360
        .size:           8
        .value_kind:     hidden_multigrid_sync_arg
    .group_segment_fixed_size: 132112
    .kernarg_segment_align: 8
    .kernarg_segment_size: 528
    .language:       OpenCL C
    .language_version:
      - 2
      - 0
    .max_flat_workgroup_size: 512
    .name:           _Z6k_mega6Params
    .private_segment_fixed_size: 0
    .sgpr_count:     108
    .sgpr_spill_count: 158
    .symbol:         _Z6k_mega6Params.kd
    .uniform_work_group_size: 1
    .uses_dynamic_stack: false
    .vgpr_count:     256
    .vgpr_spill_count: 0
    .wavefront_size: 64
